# v93 + XCD-local attention items: workgroup-id bit-field swap so the 8 workgroups sharing one (batch, head) K/V stream run on one XCD and reuse it from that L2
# speedup vs baseline: 1.0009x; 1.0009x over previous
.LBB0_774:
	s_waitcnt vmcnt(0)
	v_mov_b32_e32 v3, v0
	s_mov_b32 s2, s10
	s_load_dword s3, s[0:1], 0xe0
	s_waitcnt lgkmcnt(0)
	s_cmp_lg_u32 s3, 0x100
	s_cbranch_scc1 .Lxcd_keep_0
	s_and_b32 s2, s10, 7
	s_lshl_b32 s2, s2, 3
	s_bfe_u32 s3, s10, 0x30003
	s_or_b32 s2, s2, s3
	s_and_b32 s3, s10, 0xc0
	s_or_b32 s2, s2, s3
.Lxcd_keep_0:
	v_ashrrev_i32_e32 v2, 8, v3
	s_movk_i32 s11, 0x600
	v_lshl_add_u32 v1, s2, 1, v2
	v_cmp_gt_i32_e32 vcc, s11, v1
	s_and_saveexec_b64 s[22:23], vcc
	s_cbranch_execz .LBB0_898
	s_load_dword s3, s[0:1], 0xe0
	s_load_dwordx4 s[12:15], s[16:17], 0xc8
	v_lshrrev_b32_e32 v3, 8, v3
	s_mov_b32 s4, 0x10800
	v_mul_i32_i24_e32 v161, 0x10800, v2
	s_waitcnt lgkmcnt(0)
	s_lshl_b32 s33, s3, 1
	s_add_u32 s24, s14, 0x17f0000
	s_addc_u32 s25, s15, 0
	s_add_u32 s26, s14, 0xc3b0000
	s_addc_u32 s27, s15, 0
	s_add_u32 s28, s14, 0x8130000
	s_addc_u32 s29, s15, 0
	s_add_u32 s30, s14, 0xaa30000
	s_addc_u32 s31, s15, 0
	s_add_u32 s34, s14, 0x40000
	s_addc_u32 s35, s15, 0
	s_add_u32 s36, s14, 0x37f0000
	s_addc_u32 s37, s15, 0
	s_add_u32 s40, s14, 0xd4b0000
	s_addc_u32 s41, s15, 0
	s_add_u32 s12, s12, 0x4a00000
	s_addc_u32 s13, s13, 0
	s_lshl_b32 s2, s2, 1
	v_add_u16_e32 v169, s2, v3
	v_mov_b32_e32 v3, 0x4800
	v_mad_i32_i24 v173, v2, s4, v3
	s_mov_b32 s44, 0x358637bd
	v_mbcnt_lo_u32_b32 v2, -1, 0
	v_mbcnt_hi_u32_b32 v177, -1, v2
	s_mov_b32 s54, 0xfff80000
	v_and_b32_e32 v2, 64, v177
	s_mov_b64 s[38:39], 0xd4b0000
	s_mov_b64 s[42:43], 0
	s_movk_i32 s70, 0x200
	s_movk_i32 s71, 0xff
	s_movk_i32 s72, 0x60
	v_mov_b32_e32 v3, 0
	s_mov_b32 s45, 0x3c2aaaab
	s_mov_b32 s73, 0x800000
	s_mov_b32 s74, 0x8800
	s_movk_i32 s75, 0xab
	s_movk_i32 s76, 0x100
	s_movk_i32 s77, 0x88
	s_movk_i32 s78, 0x3400
	s_mov_b64 s[46:47], 0x18000
	s_mov_b64 s[48:49], 0x30000
	s_mov_b32 s79, 0x8a00
	s_mov_b32 s80, 0xe000
	s_movk_i32 s81, 0x8a0
	s_movk_i32 s82, 0x70
	s_mov_b32 s83, 0xbfb8aa3b
	s_mov_b32 s84, 0x42ce8ed0
	s_mov_b32 s85, 0xc2b17218
	s_mov_b32 s86, 0x7f800000
	s_mov_b32 s87, 0x3f2aaaab
	v_mov_b32_e32 v174, 0x3ecc95a3
	s_mov_b32 s88, 0x3f317218
	s_mov_b32 s89, 0x33800000
	s_mov_b32 s90, 0x3fb8aa3b
	s_mov_b32 s91, 0xc2ce8ed0
	s_mov_b32 s92, 0x42b17218
	s_mov_b32 s93, 0xd4b0000
	s_mov_b64 s[50:51], 0x80000
	s_mov_b64 s[52:53], 0xd4b4000
	s_mov_b32 s94, 0xd4b4000
	s_mov_b32 s55, -1
	s_mov_b64 s[58:59], 0x10000
	s_movk_i32 s95, 0x1140
	v_mov_b32_e32 v175, 0x358637bd
	s_mov_b64 s[60:61], 0x17f0600
	s_mov_b32 s96, 0x17f0000
	s_movk_i32 s97, 0x5ff
	v_mov_b32_e32 v176, 0x2000
	v_xor_b32_e32 v178, 32, v177
	v_add_u32_e32 v179, 64, v2
	v_mov_b32_e32 v180, 4
	v_mov_b32_e32 v181, 0x70
	v_mov_b32_e32 v182, 0x7f800000
	v_mov_b32_e32 v183, 6
	v_mov_b32_e32 v184, 1
	s_branch .LBB0_778

.Lxcd_keep_1:
	v_ashrrev_i32_e32 v2, 8, v3
	s_movk_i32 s11, 0x600
	v_lshl_add_u32 v1, s2, 1, v2
	v_cmp_gt_i32_e32 vcc, s11, v1
	s_and_saveexec_b64 s[22:23], vcc
	s_cbranch_execz .LBB0_2141
	s_load_dword s3, s[0:1], 0xe0
	s_load_dwordx4 s[12:15], s[16:17], 0xc8
	v_lshrrev_b32_e32 v3, 8, v3
	s_mov_b32 s4, 0x10800
	v_mul_i32_i24_e32 v161, 0x10800, v2
	s_waitcnt lgkmcnt(0)
	s_lshl_b32 s33, s3, 1
	s_add_u32 s24, s14, 0x17f0000
	s_addc_u32 s25, s15, 0
	s_add_u32 s26, s14, 0xc3b0000
	s_addc_u32 s27, s15, 0
	s_add_u32 s28, s14, 0x8130000
	s_addc_u32 s29, s15, 0
	s_add_u32 s30, s14, 0xaa30000
	s_addc_u32 s31, s15, 0
	s_add_u32 s34, s14, 0x40000
	s_addc_u32 s35, s15, 0
	s_add_u32 s36, s14, 0x37f0000
	s_addc_u32 s37, s15, 0
	s_add_u32 s40, s14, 0xd4b0000
	s_addc_u32 s41, s15, 0
	s_add_u32 s12, s12, 0x4a00000
	s_addc_u32 s13, s13, 0
	s_lshl_b32 s2, s2, 1
	v_add_u16_e32 v169, s2, v3
	v_mov_b32_e32 v3, 0x4800
	v_mad_i32_i24 v173, v2, s4, v3
	s_mov_b32 s44, 0x358637bd
	v_mbcnt_lo_u32_b32 v2, -1, 0
	v_mbcnt_hi_u32_b32 v177, -1, v2
	s_mov_b32 s54, 0xfff80000
	v_and_b32_e32 v2, 64, v177
	s_mov_b64 s[38:39], 0xd4b0000
	s_mov_b64 s[42:43], 0
	s_movk_i32 s70, 0x200
	s_movk_i32 s71, 0x60
	v_mov_b32_e32 v3, 0
	s_mov_b32 s45, 0x3c2aaaab
	s_mov_b32 s72, 0x800000
	s_mov_b32 s73, 0x8800
	s_movk_i32 s74, 0xab
	s_movk_i32 s75, 0x100
	s_movk_i32 s76, 0x88
	s_movk_i32 s77, 0x3400
	s_mov_b64 s[46:47], 0x18000
	s_mov_b64 s[48:49], 0x30000
	s_mov_b32 s78, 0x8a00
	s_mov_b32 s79, 0xe000
	s_movk_i32 s80, 0x8a0
	s_movk_i32 s81, 0x70
	s_mov_b32 s82, 0xbfb8aa3b
	s_mov_b32 s83, 0x42ce8ed0
	s_mov_b32 s84, 0xc2b17218
	s_mov_b32 s85, 0x7f800000
	s_mov_b32 s86, 0x3f2aaaab
	v_mov_b32_e32 v174, 0x3ecc95a3
	s_mov_b32 s87, 0x3f317218
	s_mov_b32 s88, 0x33800000
	s_mov_b32 s89, 0x3fb8aa3b
	s_mov_b32 s90, 0xc2ce8ed0
	s_mov_b32 s91, 0x42b17218
	s_mov_b32 s93, 0xd4b0000
	s_mov_b64 s[50:51], 0x80000
	s_mov_b64 s[52:53], 0xd4b4000
	s_mov_b32 s94, 0xd4b4000
	s_mov_b32 s55, -1
	s_mov_b64 s[56:57], 0x20000
	s_mov_b64 s[58:59], 0x4000
	s_movk_i32 s95, 0x1140
	v_mov_b32_e32 v175, 0x358637bd
	s_mov_b64 s[60:61], 0x17f0600
	s_mov_b32 s96, 0x17f0000
	s_movk_i32 s97, 0x5ff
	v_mov_b32_e32 v176, 0x2000
	v_xor_b32_e32 v178, 32, v177
	v_add_u32_e32 v179, 64, v2
	v_mov_b32_e32 v180, 4
	v_mov_b32_e32 v181, 0x70
	v_mov_b32_e32 v182, 0x7f800000
	v_mov_b32_e32 v183, 6
	v_mov_b32_e32 v184, 1
	s_branch .LBB0_2021
